# speedup vs baseline: 1.0009x; 1.0009x over previous
; #define WAIT_V(n) asm volatile("s_waitcnt vmcnt(" #n ")" ::: "memory")
; #define BAR __builtin_amdgcn_s_barrier()
; template <int MODE>
; __device__ __forceinline__ void gemm_tile(const int ph, const int which, const int pm, const int pn) {
;     ...
;   f32x4 acc[2][2][4][2] = {};
;   bf16x8 At[4][2], B0[2][2], B1[2][2];
;   const int nt = K / BK;
;   const int brow = browA;
;   STAGE(SB(0, 0), RB, bcol, 0);
;   STAGE(SA(0, 0), RA, brow, 0);
;   STAGE(SB(0, 1), RB, bcolB, 0);
;   STAGE(SA(0, 1), RA, brow + HALF, 0);
;   if (wr == 1) BAR;
;   WAIT_V(4);
;   BAR;
;   STAGE(SB(1, 0), RB, bcol, 1);
;   STAGE(SA(1, 0), RA, brow, 1);
;   STAGE(SB(1, 1), RB, bcolB, 1);
;   WAIT_V(6);
;   BAR;
.LBB0_130:
	s_or_b64 exec, exec, s[2:3]
	v_add_u32_e32 v149, 0x18000, v139
	v_add_u32_e32 v150, 0x1a000, v139
	v_readfirstlane_b32 s6, v149
	s_or_b32 s3, s19, 0x80
	s_mov_b32 m0, s6
	v_readfirstlane_b32 s6, v150
	v_add_u32_e32 v151, 0x8000, v139
	s_waitcnt vmcnt(4)
	s_barrier
	buffer_load_dwordx4 v138, s[68:71], s3 offen lds
	s_add_i32 s3, s3, s10
	s_mov_b32 m0, s6
	v_readfirstlane_b32 s12, v151
	v_add_u32_e32 v152, 0xa000, v139
	buffer_load_dwordx4 v138, s[68:71], s3 offen lds
	s_or_b32 s3, s17, 0x80
	s_mov_b32 s6, s70
	s_mov_b32 s7, s71
	s_mov_b32 m0, s12
	v_readfirstlane_b32 s12, v152
	v_add_u32_e32 v154, 0x1c000, v139
	buffer_load_dwordx4 v138, s[4:7], s3 offen lds
	s_add_i32 s3, s3, s10
	s_mov_b32 m0, s12
	v_readfirstlane_b32 s12, v154
	v_add_u32_e32 v156, 0x1e000, v139
	buffer_load_dwordx4 v138, s[4:7], s3 offen lds
	s_or_b32 s3, s16, 0x80
	s_mov_b32 m0, s12
	v_readfirstlane_b32 s12, v156
	buffer_load_dwordx4 v138, s[68:71], s3 offen lds
	s_add_i32 s3, s3, s10
	s_mov_b32 m0, s12
	v_and_b32_e32 v3, 15, v0
	buffer_load_dwordx4 v138, s[68:71], s3 offen lds
	v_bfe_u32 v132, v0, 4, 2
	v_lshlrev_b32_e32 v5, 4, v132
	v_lshlrev_b32_e32 v6, 6, v3
	v_lshlrev_b32_e32 v8, 2, v0
	v_or_b32_e32 v7, v5, v6
	v_and_b32_e32 v8, 32, v8
	s_mov_b32 s3, 0x10000
	v_bitop3_b32 v9, v7, s3, v8 bitop3:0xde
	s_mov_b32 s3, 0x14000
	v_bitop3_b32 v10, v7, s3, v8 bitop3:0xde
	s_mov_b32 s3, 0x18000
	v_bitop3_b32 v11, v7, s3, v8 bitop3:0xde
	s_mov_b32 s3, 0x1c000
	s_lshl_b32 s12, s22, 1
	v_bitop3_b32 v7, v7, s3, v8 bitop3:0xde
	v_lshl_or_b32 v133, v2, 6, v3
	v_lshlrev_b32_e32 v3, 13, v2
	v_lshlrev_b32_e32 v2, 6, v0
	s_add_i32 s3, s12, 0x180
	s_addk_i32 s12, 0x80
	v_bfe_u32 v131, v0, 6, 2
	v_and_b32_e32 v2, 0x3c0, v2
	s_lshl_b32 s17, s18, 1
	s_mul_i32 s19, s26, s12
	s_lshl_b32 s12, s24, 1
	s_lshr_b32 s2, s26, 6
	v_lshlrev_b32_e32 v4, 12, v131
	v_bitop3_b32 v6, v5, v8, v6 bitop3:0x36
	v_bitop3_b32 v5, v2, v8, v5 bitop3:0x36
	v_or_b32_e32 v8, 0x800, v3
	v_or_b32_e32 v12, 0x1000, v3
	v_or_b32_e32 v13, 0x1800, v3
	s_lshl_b32 s13, s26, 1
	s_add_i32 s16, s22, 0x80
	s_addk_i32 s17, 0x80
	s_addk_i32 s12, 0x80
	v_mov_b32_e32 v2, 0
	v_lshrrev_b32_e32 v130, 4, v0
	s_add_i32 s2, s2, -2
	v_add_u32_e32 v155, 0xc000, v139
	v_add_u32_e32 v153, 0xe000, v139
	s_mul_i32 s3, s26, s3
	s_mul_i32 s16, s13, s16
	s_mul_i32 s17, s26, s17
	s_mul_i32 s18, s13, s18
	s_mul_i32 s22, s13, s22
	s_mul_i32 s23, s26, s12
	s_mul_i32 s24, s13, s24
	s_mov_b32 s25, 0
	v_add_u32_e32 v158, v9, v4
	v_add_u32_e32 v137, v6, v3
	v_add_u32_e32 v136, v5, v8
	v_add_u32_e32 v135, v5, v12
	v_add_u32_e32 v134, v5, v13
	v_add_u32_e32 v157, v10, v4
	v_add_u32_e32 v146, v11, v4
	v_add_u32_e32 v140, v7, v4
	s_mov_b32 s27, 0
	v_mov_b32_e32 v3, v2
	v_mov_b32_e32 v4, v2
	v_mov_b32_e32 v5, v2
	v_mov_b32_e32 v6, v2
	v_mov_b32_e32 v7, v2
	v_mov_b32_e32 v8, v2
	v_mov_b32_e32 v9, v2
	v_mov_b32_e32 v10, v2
	v_mov_b32_e32 v11, v2
	v_mov_b32_e32 v12, v2
	v_mov_b32_e32 v13, v2
	v_mov_b32_e32 v14, v2
	v_mov_b32_e32 v15, v2
	v_mov_b32_e32 v16, v2
	v_mov_b32_e32 v17, v2
	v_mov_b32_e32 v18, v2
	v_mov_b32_e32 v19, v2
	v_mov_b32_e32 v20, v2
	v_mov_b32_e32 v21, v2
	v_mov_b32_e32 v22, v2
	v_mov_b32_e32 v23, v2
	v_mov_b32_e32 v24, v2
	v_mov_b32_e32 v25, v2
	v_mov_b32_e32 v26, v2
	v_mov_b32_e32 v27, v2
	v_mov_b32_e32 v28, v2
	v_mov_b32_e32 v29, v2
	v_mov_b32_e32 v30, v2
	v_mov_b32_e32 v31, v2
	v_mov_b32_e32 v32, v2
	v_mov_b32_e32 v33, v2
	v_mov_b32_e32 v34, v2
	v_mov_b32_e32 v35, v2
	v_mov_b32_e32 v36, v2
	v_mov_b32_e32 v37, v2
	v_mov_b32_e32 v38, v2
	v_mov_b32_e32 v39, v2
	v_mov_b32_e32 v40, v2
	v_mov_b32_e32 v41, v2
	v_mov_b32_e32 v42, v2
	v_mov_b32_e32 v43, v2
	v_mov_b32_e32 v44, v2
	v_mov_b32_e32 v45, v2
	v_mov_b32_e32 v46, v2
	v_mov_b32_e32 v47, v2
	v_mov_b32_e32 v48, v2
	v_mov_b32_e32 v49, v2
	v_mov_b32_e32 v50, v2
	v_mov_b32_e32 v51, v2
	v_mov_b32_e32 v52, v2
	v_mov_b32_e32 v53, v2
	v_mov_b32_e32 v54, v2
	v_mov_b32_e32 v55, v2
	v_mov_b32_e32 v56, v2
	v_mov_b32_e32 v57, v2
	v_mov_b32_e32 v58, v2
	v_mov_b32_e32 v59, v2
	v_mov_b32_e32 v60, v2
	v_mov_b32_e32 v61, v2
	v_mov_b32_e32 v62, v2
	v_mov_b32_e32 v63, v2
	v_mov_b32_e32 v64, v2
	v_mov_b32_e32 v65, v2
	v_mov_b32_e32 v66, v2
	v_mov_b32_e32 v67, v2
	v_mov_b32_e32 v68, v2
	v_mov_b32_e32 v69, v2
	v_mov_b32_e32 v70, v2
	v_mov_b32_e32 v71, v2
	v_mov_b32_e32 v72, v2
	v_mov_b32_e32 v73, v2
	v_mov_b32_e32 v74, v2
	v_mov_b32_e32 v75, v2
	v_mov_b32_e32 v76, v2
	v_mov_b32_e32 v77, v2
	v_mov_b32_e32 v78, v2
	v_mov_b32_e32 v79, v2
	v_mov_b32_e32 v80, v2
	v_mov_b32_e32 v81, v2
	v_mov_b32_e32 v82, v2
	v_mov_b32_e32 v83, v2
	v_mov_b32_e32 v84, v2
	v_mov_b32_e32 v85, v2
	v_mov_b32_e32 v86, v2
	v_mov_b32_e32 v87, v2
	v_mov_b32_e32 v88, v2
	v_mov_b32_e32 v89, v2
	v_mov_b32_e32 v90, v2
	v_mov_b32_e32 v91, v2
	v_mov_b32_e32 v92, v2
	v_mov_b32_e32 v93, v2
	v_mov_b32_e32 v94, v2
	v_mov_b32_e32 v95, v2
	v_mov_b32_e32 v96, v2
	v_mov_b32_e32 v97, v2
	v_mov_b32_e32 v98, v2
	v_mov_b32_e32 v99, v2
	v_mov_b32_e32 v100, v2
	v_mov_b32_e32 v101, v2
	v_mov_b32_e32 v102, v2
	v_mov_b32_e32 v103, v2
	v_mov_b32_e32 v104, v2
	v_mov_b32_e32 v105, v2
	v_mov_b32_e32 v106, v2
	v_mov_b32_e32 v107, v2
	v_mov_b32_e32 v108, v2
	v_mov_b32_e32 v109, v2
	v_mov_b32_e32 v110, v2
	v_mov_b32_e32 v111, v2
	v_mov_b32_e32 v112, v2
	v_mov_b32_e32 v113, v2
	v_mov_b32_e32 v114, v2
	v_mov_b32_e32 v115, v2
	v_mov_b32_e32 v116, v2
	v_mov_b32_e32 v117, v2
	v_mov_b32_e32 v118, v2
	v_mov_b32_e32 v119, v2
	v_mov_b32_e32 v120, v2
	v_mov_b32_e32 v121, v2
	v_mov_b32_e32 v122, v2
	v_mov_b32_e32 v123, v2
	v_mov_b32_e32 v124, v2
	v_mov_b32_e32 v125, v2
	v_mov_b32_e32 v126, v2
	v_mov_b32_e32 v127, v2
	v_mov_b32_e32 v128, v2
	v_mov_b32_e32 v129, v2
	s_waitcnt vmcnt(6)
	s_barrier

; #define WAIT_V(n) asm volatile("s_waitcnt vmcnt(" #n ")" ::: "memory")
; #define BAR __builtin_amdgcn_s_barrier()
; template <int MODE>
; __device__ __forceinline__ void gemm_tile(const int ph, const int which, const int pm, const int pn) {
;     ...
;   f32x4 acc[2][2][4][2] = {};
;   bf16x8 At[4][2], B0[2][2], B1[2][2];
;   const int nt = K / BK;
;   const int brow = browA;
;   STAGE(SB(0, 0), RB, bcol, 0);
;   STAGE(SA(0, 0), RA, brow, 0);
;   STAGE(SB(0, 1), RB, bcolB, 0);
;   STAGE(SA(0, 1), RA, brow + HALF, 0);
;   if (wr == 1) BAR;
;   WAIT_V(4);
;   BAR;
;   STAGE(SB(1, 0), RB, bcol, 1);
;   STAGE(SA(1, 0), RA, brow, 1);
;   STAGE(SB(1, 1), RB, bcolB, 1);
;   WAIT_V(6);
;   BAR;
.LBB0_217:
	s_or_b64 exec, exec, s[6:7]
	v_add_u32_e32 v147, 0x18000, v136
	v_add_u32_e32 v148, 0x1a000, v136
	v_readfirstlane_b32 s7, v147
	s_or_b32 s6, s18, 0x80
	s_mov_b32 m0, s7
	v_readfirstlane_b32 s7, v148
	v_add_u32_e32 v149, 0x8000, v136
	s_waitcnt vmcnt(4)
	s_barrier
	buffer_load_dwordx4 v135, s[68:71], s6 offen lds
	s_add_i32 s6, s6, s10
	s_mov_b32 m0, s7
	s_or_b32 s13, s17, 0x80
	v_readfirstlane_b32 s17, v149
	v_add_u32_e32 v150, 0xa000, v136
	buffer_load_dwordx4 v135, s[68:71], s6 offen lds
	s_mov_b32 s6, s70
	s_mov_b32 s7, s71
	s_mov_b32 m0, s17
	v_readfirstlane_b32 s17, v150
	buffer_load_dwordx4 v135, s[4:7], s13 offen lds
	s_add_i32 s13, s13, s10
	s_mov_b32 m0, s17
	v_add_u32_e32 v152, 0x1c000, v136
	buffer_load_dwordx4 v135, s[4:7], s13 offen lds
	s_or_b32 s13, s16, 0x80
	v_readfirstlane_b32 s16, v152
	v_add_u32_e32 v154, 0x1e000, v136
	s_mov_b32 m0, s16
	v_readfirstlane_b32 s16, v154
	buffer_load_dwordx4 v135, s[68:71], s13 offen lds
	s_add_i32 s13, s13, s10
	s_mov_b32 m0, s16
	v_and_b32_e32 v3, 15, v0
	buffer_load_dwordx4 v135, s[68:71], s13 offen lds
	s_lshr_b32 s12, s28, 6
	v_and_b32_e32 v5, 48, v0
	v_lshlrev_b32_e32 v6, 6, v3
	v_lshlrev_b32_e32 v8, 2, v0
	s_add_i32 s16, s12, -2
	v_or_b32_e32 v7, v6, v5
	v_and_b32_e32 v8, 32, v8
	s_mov_b32 s12, 0x10000
	v_bitop3_b32 v9, v7, s12, v8 bitop3:0xde
	s_mov_b32 s12, 0x14000
	v_bitop3_b32 v10, v7, s12, v8 bitop3:0xde
	s_mov_b32 s12, 0x18000
	v_bitop3_b32 v11, v7, s12, v8 bitop3:0xde
	s_mov_b32 s12, 0x1c000
	v_bitop3_b32 v7, v7, s12, v8 bitop3:0xde
	s_lshl_b32 s12, s22, 1
	v_lshl_or_b32 v130, v2, 6, v3
	v_lshlrev_b32_e32 v3, 13, v2
	v_lshlrev_b32_e32 v2, 6, v0
	s_add_i32 s13, s12, 0x180
	s_addk_i32 s12, 0x80
	v_bfe_u32 v138, v0, 6, 2
	v_and_b32_e32 v2, 0x3c0, v2
	s_lshl_b32 s19, s20, 1
	s_mul_i32 s21, s28, s12
	s_lshl_b32 s12, s26, 1
	v_lshlrev_b32_e32 v4, 12, v138
	v_bitop3_b32 v6, v6, v8, v5 bitop3:0x36
	v_bitop3_b32 v5, v2, v8, v5 bitop3:0x36
	v_or_b32_e32 v8, 0x800, v3
	v_or_b32_e32 v12, 0x1000, v3
	v_or_b32_e32 v13, 0x1800, v3
	s_mul_i32 s17, s28, s13
	s_lshl_b32 s13, s28, 1
	s_add_i32 s18, s22, 0x80
	s_addk_i32 s19, 0x80
	s_addk_i32 s12, 0x80
	v_mov_b32_e32 v2, 0
	v_add_u32_e32 v153, 0xc000, v136
	v_add_u32_e32 v151, 0xe000, v136
	s_mul_i32 s18, s13, s18
	s_mul_i32 s19, s28, s19
	s_mul_i32 s20, s13, s20
	s_mul_i32 s22, s13, s22
	s_mul_i32 s25, s28, s12
	s_mul_i32 s26, s13, s26
	s_mov_b32 s27, 0
	v_add_u32_e32 v156, v9, v4
	v_add_u32_e32 v134, v6, v3
	v_add_u32_e32 v133, v5, v8
	v_add_u32_e32 v132, v5, v12
	v_add_u32_e32 v131, v5, v13
	v_add_u32_e32 v155, v10, v4
	v_add_u32_e32 v144, v11, v4
	v_add_u32_e32 v137, v7, v4
	s_mov_b32 vcc_lo, 0
	v_mov_b32_e32 v3, v2
	v_mov_b32_e32 v4, v2
	v_mov_b32_e32 v5, v2
	v_mov_b32_e32 v6, v2
	v_mov_b32_e32 v7, v2
	v_mov_b32_e32 v8, v2
	v_mov_b32_e32 v9, v2
	v_mov_b32_e32 v10, v2
	v_mov_b32_e32 v11, v2
	v_mov_b32_e32 v12, v2
	v_mov_b32_e32 v13, v2
	v_mov_b32_e32 v14, v2
	v_mov_b32_e32 v15, v2
	v_mov_b32_e32 v16, v2
	v_mov_b32_e32 v17, v2
	v_mov_b32_e32 v18, v2
	v_mov_b32_e32 v19, v2
	v_mov_b32_e32 v20, v2
	v_mov_b32_e32 v21, v2
	v_mov_b32_e32 v22, v2
	v_mov_b32_e32 v23, v2
	v_mov_b32_e32 v24, v2
	v_mov_b32_e32 v25, v2
	v_mov_b32_e32 v26, v2
	v_mov_b32_e32 v27, v2
	v_mov_b32_e32 v28, v2
	v_mov_b32_e32 v29, v2
	v_mov_b32_e32 v30, v2
	v_mov_b32_e32 v31, v2
	v_mov_b32_e32 v32, v2
	v_mov_b32_e32 v33, v2
	v_mov_b32_e32 v34, v2
	v_mov_b32_e32 v35, v2
	v_mov_b32_e32 v36, v2
	v_mov_b32_e32 v37, v2
	v_mov_b32_e32 v38, v2
	v_mov_b32_e32 v39, v2
	v_mov_b32_e32 v40, v2
	v_mov_b32_e32 v41, v2
	v_mov_b32_e32 v42, v2
	v_mov_b32_e32 v43, v2
	v_mov_b32_e32 v44, v2
	v_mov_b32_e32 v45, v2
	v_mov_b32_e32 v46, v2
	v_mov_b32_e32 v47, v2
	v_mov_b32_e32 v48, v2
	v_mov_b32_e32 v49, v2
	v_mov_b32_e32 v50, v2
	v_mov_b32_e32 v51, v2
	v_mov_b32_e32 v52, v2
	v_mov_b32_e32 v53, v2
	v_mov_b32_e32 v54, v2
	v_mov_b32_e32 v55, v2
	v_mov_b32_e32 v56, v2
	v_mov_b32_e32 v57, v2
	v_mov_b32_e32 v58, v2
	v_mov_b32_e32 v59, v2
	v_mov_b32_e32 v60, v2
	v_mov_b32_e32 v61, v2
	v_mov_b32_e32 v62, v2
	v_mov_b32_e32 v63, v2
	v_mov_b32_e32 v64, v2
	v_mov_b32_e32 v65, v2
	v_mov_b32_e32 v66, v2
	v_mov_b32_e32 v67, v2
	v_mov_b32_e32 v68, v2
	v_mov_b32_e32 v69, v2
	v_mov_b32_e32 v70, v2
	v_mov_b32_e32 v71, v2
	v_mov_b32_e32 v72, v2
	v_mov_b32_e32 v73, v2
	v_mov_b32_e32 v74, v2
	v_mov_b32_e32 v75, v2
	v_mov_b32_e32 v76, v2
	v_mov_b32_e32 v77, v2
	v_mov_b32_e32 v78, v2
	v_mov_b32_e32 v79, v2
	v_mov_b32_e32 v80, v2
	v_mov_b32_e32 v81, v2
	v_mov_b32_e32 v82, v2
	v_mov_b32_e32 v83, v2
	v_mov_b32_e32 v84, v2
	v_mov_b32_e32 v85, v2
	v_mov_b32_e32 v86, v2
	v_mov_b32_e32 v87, v2
	v_mov_b32_e32 v88, v2
	v_mov_b32_e32 v89, v2
	v_mov_b32_e32 v90, v2
	v_mov_b32_e32 v91, v2
	v_mov_b32_e32 v92, v2
	v_mov_b32_e32 v93, v2
	v_mov_b32_e32 v94, v2
	v_mov_b32_e32 v95, v2
	v_mov_b32_e32 v96, v2
	v_mov_b32_e32 v97, v2
	v_mov_b32_e32 v98, v2
	v_mov_b32_e32 v99, v2
	v_mov_b32_e32 v100, v2
	v_mov_b32_e32 v101, v2
	v_mov_b32_e32 v102, v2
	v_mov_b32_e32 v103, v2
	v_mov_b32_e32 v104, v2
	v_mov_b32_e32 v105, v2
	v_mov_b32_e32 v106, v2
	v_mov_b32_e32 v107, v2
	v_mov_b32_e32 v108, v2
	v_mov_b32_e32 v109, v2
	v_mov_b32_e32 v110, v2
	v_mov_b32_e32 v111, v2
	v_mov_b32_e32 v112, v2
	v_mov_b32_e32 v113, v2
	v_mov_b32_e32 v114, v2
	v_mov_b32_e32 v115, v2
	v_mov_b32_e32 v116, v2
	v_mov_b32_e32 v117, v2
	v_mov_b32_e32 v118, v2
	v_mov_b32_e32 v119, v2
	v_mov_b32_e32 v120, v2
	v_mov_b32_e32 v121, v2
	v_mov_b32_e32 v122, v2
	v_mov_b32_e32 v123, v2
	v_mov_b32_e32 v124, v2
	v_mov_b32_e32 v125, v2
	v_mov_b32_e32 v126, v2
	v_mov_b32_e32 v127, v2
	v_mov_b32_e32 v128, v2
	v_mov_b32_e32 v129, v2
	s_waitcnt vmcnt(6)
	s_barrier

; #define WAIT_V(n) asm volatile("s_waitcnt vmcnt(" #n ")" ::: "memory")
; #define BAR __builtin_amdgcn_s_barrier()
; template <int MODE>
; __device__ __forceinline__ void gemm_tile(const int ph, const int which, const int pm, const int pn) {
;     ...
;   f32x4 acc[2][2][4][2] = {};
;   bf16x8 At[4][2], B0[2][2], B1[2][2];
;   const int nt = K / BK;
;   const int brow = browA;
;   STAGE(SB(0, 0), RB, bcol, 0);
;   STAGE(SA(0, 0), RA, brow, 0);
;   STAGE(SB(0, 1), RB, bcolB, 0);
;   STAGE(SA(0, 1), RA, brow + HALF, 0);
;   if (wr == 1) BAR;
;   WAIT_V(4);
;   BAR;
;   STAGE(SB(1, 0), RB, bcol, 1);
;   STAGE(SA(1, 0), RA, brow, 1);
;   STAGE(SB(1, 1), RB, bcolB, 1);
;   WAIT_V(6);
;   BAR;
.LBB0_369:
	s_or_b64 exec, exec, s[2:3]
	v_add_u32_e32 v145, 0x18000, v131
	v_add_u32_e32 v146, 0x1a000, v131
	v_readfirstlane_b32 s6, v145
	s_or_b32 s3, s17, 0x80
	s_mov_b32 m0, s6
	v_readfirstlane_b32 s6, v146
	s_waitcnt vmcnt(4)
	s_barrier
	buffer_load_dwordx4 v130, s[68:71], s3 offen lds
	s_add_i32 s3, s3, s8
	s_mov_b32 m0, s6
	v_add_u32_e32 v147, 0x8000, v131
	buffer_load_dwordx4 v130, s[68:71], s3 offen lds
	s_or_b32 s3, s11, 0x80
	v_readfirstlane_b32 s11, v147
	v_add_u32_e32 v148, 0xa000, v131
	s_mov_b32 s6, s70
	s_mov_b32 s7, s71
	s_mov_b32 m0, s11
	v_readfirstlane_b32 s11, v148
	buffer_load_dwordx4 v130, s[4:7], s3 offen lds
	s_add_i32 s3, s3, s8
	s_mov_b32 m0, s11
	v_add_u32_e32 v150, 0x1c000, v131
	buffer_load_dwordx4 v130, s[4:7], s3 offen lds
	s_or_b32 s3, s10, 0x80
	v_readfirstlane_b32 s10, v150
	v_add_u32_e32 v152, 0x1e000, v131
	s_mov_b32 m0, s10
	v_readfirstlane_b32 s10, v152
	buffer_load_dwordx4 v130, s[68:71], s3 offen lds
	s_add_i32 s3, s3, s8
	s_mov_b32 m0, s10
	v_and_b32_e32 v2, 15, v164
	buffer_load_dwordx4 v130, s[68:71], s3 offen lds
	v_bfe_u32 v162, v164, 4, 2
	v_lshlrev_b32_e32 v4, 4, v162
	v_lshlrev_b32_e32 v5, 6, v2
	v_lshlrev_b32_e32 v7, 2, v164
	v_or_b32_e32 v6, v4, v5
	v_and_b32_e32 v7, 32, v7
	s_mov_b32 s3, 0x10000
	v_bitop3_b32 v8, v6, s3, v7 bitop3:0xde
	s_mov_b32 s3, 0x14000
	v_bitop3_b32 v9, v6, s3, v7 bitop3:0xde
	s_mov_b32 s3, 0x18000
	v_bitop3_b32 v10, v6, s3, v7 bitop3:0xde
	s_mov_b32 s3, 0x1c000
	s_lshl_b32 s12, s18, 1
	v_bitop3_b32 v6, v6, s3, v7 bitop3:0xde
	v_lshl_or_b32 v163, v167, 6, v2
	v_lshlrev_b32_e32 v2, 6, v164
	s_add_i32 s3, s12, 0x180
	s_addk_i32 s12, 0x80
	v_bfe_u32 v0, v164, 6, 2
	v_lshlrev_b32_e32 v11, 13, v167
	v_and_b32_e32 v2, 0x3c0, v2
	s_lshl_b32 s11, s16, 1
	s_mul_i32 s17, s26, s12
	s_lshl_b32 s12, s20, 1
	s_lshr_b32 s2, s26, 6
	v_lshlrev_b32_e32 v3, 12, v0
	v_bitop3_b32 v5, v4, v7, v5 bitop3:0x36
	v_bitop3_b32 v4, v2, v7, v4 bitop3:0x36
	v_or_b32_e32 v7, 0x800, v11
	v_or_b32_e32 v12, 0x1000, v11
	v_or_b32_e32 v13, 0x1800, v11
	s_lshl_b32 s13, s26, 1
	s_add_i32 s10, s18, 0x80
	s_addk_i32 s11, 0x80
	s_addk_i32 s12, 0x80
	v_mov_b32_e32 v2, 0
	s_add_i32 s2, s2, -2
	v_add_u32_e32 v151, 0xc000, v131
	v_add_u32_e32 v149, 0xe000, v131
	s_mul_i32 s3, s26, s3
	s_mul_i32 s10, s13, s10
	s_mul_i32 s11, s26, s11
	s_mul_i32 s16, s13, s16
	s_mul_i32 s18, s13, s18
	s_mul_i32 s19, s26, s12
	s_mul_i32 s20, s13, s20
	s_mov_b32 s21, 0
	v_add_u32_e32 v154, v8, v3
	v_add_u32_e32 v141, v5, v11
	v_add_u32_e32 v140, v4, v7
	v_add_u32_e32 v139, v4, v12
	v_add_u32_e32 v138, v4, v13
	v_add_u32_e32 v153, v9, v3
	v_add_u32_e32 v137, v10, v3
	v_add_u32_e32 v142, v6, v3
	s_mov_b32 s22, 0
	v_mov_b32_e32 v3, v2
	v_mov_b32_e32 v4, v2
	v_mov_b32_e32 v5, v2
	v_mov_b32_e32 v6, v2
	v_mov_b32_e32 v7, v2
	v_mov_b32_e32 v8, v2
	v_mov_b32_e32 v9, v2
	v_mov_b32_e32 v18, v2
	v_mov_b32_e32 v19, v2
	v_mov_b32_e32 v20, v2
	v_mov_b32_e32 v21, v2
	v_mov_b32_e32 v30, v2
	v_mov_b32_e32 v31, v2
	v_mov_b32_e32 v32, v2
	v_mov_b32_e32 v33, v2
	v_mov_b32_e32 v42, v2
	v_mov_b32_e32 v43, v2
	v_mov_b32_e32 v44, v2
	v_mov_b32_e32 v45, v2
	v_mov_b32_e32 v54, v2
	v_mov_b32_e32 v55, v2
	v_mov_b32_e32 v56, v2
	v_mov_b32_e32 v57, v2
	v_mov_b32_e32 v66, v2
	v_mov_b32_e32 v67, v2
	v_mov_b32_e32 v68, v2
	v_mov_b32_e32 v69, v2
	v_mov_b32_e32 v78, v2
	v_mov_b32_e32 v79, v2
	v_mov_b32_e32 v80, v2
	v_mov_b32_e32 v81, v2
	v_mov_b32_e32 v10, v2
	v_mov_b32_e32 v11, v2
	v_mov_b32_e32 v12, v2
	v_mov_b32_e32 v13, v2
	v_mov_b32_e32 v22, v2
	v_mov_b32_e32 v23, v2
	v_mov_b32_e32 v24, v2
	v_mov_b32_e32 v25, v2
	v_mov_b32_e32 v34, v2
	v_mov_b32_e32 v35, v2
	v_mov_b32_e32 v36, v2
	v_mov_b32_e32 v37, v2
	v_mov_b32_e32 v46, v2
	v_mov_b32_e32 v47, v2
	v_mov_b32_e32 v48, v2
	v_mov_b32_e32 v49, v2
	v_mov_b32_e32 v58, v2
	v_mov_b32_e32 v59, v2
	v_mov_b32_e32 v60, v2
	v_mov_b32_e32 v61, v2
	v_mov_b32_e32 v70, v2
	v_mov_b32_e32 v71, v2
	v_mov_b32_e32 v72, v2
	v_mov_b32_e32 v73, v2
	v_mov_b32_e32 v82, v2
	v_mov_b32_e32 v83, v2
	v_mov_b32_e32 v84, v2
	v_mov_b32_e32 v85, v2
	v_mov_b32_e32 v94, v2
	v_mov_b32_e32 v95, v2
	v_mov_b32_e32 v96, v2
	v_mov_b32_e32 v97, v2
	v_mov_b32_e32 v14, v2
	v_mov_b32_e32 v15, v2
	v_mov_b32_e32 v16, v2
	v_mov_b32_e32 v17, v2
	v_mov_b32_e32 v26, v2
	v_mov_b32_e32 v27, v2
	v_mov_b32_e32 v28, v2
	v_mov_b32_e32 v29, v2
	v_mov_b32_e32 v38, v2
	v_mov_b32_e32 v39, v2
	v_mov_b32_e32 v40, v2
	v_mov_b32_e32 v41, v2
	v_mov_b32_e32 v50, v2
	v_mov_b32_e32 v51, v2
	v_mov_b32_e32 v52, v2
	v_mov_b32_e32 v53, v2
	v_mov_b32_e32 v62, v2
	v_mov_b32_e32 v63, v2
	v_mov_b32_e32 v64, v2
	v_mov_b32_e32 v65, v2
	v_mov_b32_e32 v74, v2
	v_mov_b32_e32 v75, v2
	v_mov_b32_e32 v76, v2
	v_mov_b32_e32 v77, v2
	v_mov_b32_e32 v86, v2
	v_mov_b32_e32 v87, v2
	v_mov_b32_e32 v88, v2
	v_mov_b32_e32 v89, v2
	v_mov_b32_e32 v98, v2
	v_mov_b32_e32 v99, v2
	v_mov_b32_e32 v100, v2
	v_mov_b32_e32 v101, v2
	v_mov_b32_e32 v90, v2
	v_mov_b32_e32 v91, v2
	v_mov_b32_e32 v92, v2
	v_mov_b32_e32 v93, v2
	v_mov_b32_e32 v102, v2
	v_mov_b32_e32 v103, v2
	v_mov_b32_e32 v104, v2
	v_mov_b32_e32 v105, v2
	v_mov_b32_e32 v106, v2
	v_mov_b32_e32 v107, v2
	v_mov_b32_e32 v108, v2
	v_mov_b32_e32 v109, v2
	v_mov_b32_e32 v110, v2
	v_mov_b32_e32 v111, v2
	v_mov_b32_e32 v112, v2
	v_mov_b32_e32 v113, v2
	v_mov_b32_e32 v114, v2
	v_mov_b32_e32 v115, v2
	v_mov_b32_e32 v116, v2
	v_mov_b32_e32 v117, v2
	v_mov_b32_e32 v118, v2
	v_mov_b32_e32 v119, v2
	v_mov_b32_e32 v120, v2
	v_mov_b32_e32 v121, v2
	v_mov_b32_e32 v122, v2
	v_mov_b32_e32 v123, v2
	v_mov_b32_e32 v124, v2
	v_mov_b32_e32 v125, v2
	v_mov_b32_e32 v126, v2
	v_mov_b32_e32 v127, v2
	v_mov_b32_e32 v128, v2
	v_mov_b32_e32 v129, v2
	s_waitcnt vmcnt(6)
	s_barrier

; #define WAIT_V(n) asm volatile("s_waitcnt vmcnt(" #n ")" ::: "memory")
; #define BAR __builtin_amdgcn_s_barrier()
; template <int MODE>
; __device__ __forceinline__ void gemm_tile(const int ph, const int which, const int pm, const int pn) {
;     ...
;   f32x4 acc[2][2][4][2] = {};
;   bf16x8 At[4][2], B0[2][2], B1[2][2];
;   const int nt = K / BK;
;   const int brow = browA;
;   STAGE(SB(0, 0), RB, bcol, 0);
;   STAGE(SA(0, 0), RA, brow, 0);
;   STAGE(SB(0, 1), RB, bcolB, 0);
;   STAGE(SA(0, 1), RA, brow + HALF, 0);
;   if (wr == 1) BAR;
;   WAIT_V(4);
;   BAR;
;   STAGE(SB(1, 0), RB, bcol, 1);
;   STAGE(SA(1, 0), RA, brow, 1);
;   STAGE(SB(1, 1), RB, bcolB, 1);
;   WAIT_V(6);
;   BAR;
.LBB0_539:
	s_or_b64 exec, exec, s[2:3]
	v_add_u32_e32 v147, 0x18000, v137
	v_add_u32_e32 v148, 0x1a000, v137
	v_readfirstlane_b32 s6, v147
	s_or_b32 s3, s19, 0x80
	s_mov_b32 m0, s6
	v_readfirstlane_b32 s6, v148
	s_waitcnt vmcnt(4)
	s_barrier
	buffer_load_dwordx4 v136, s[68:71], s3 offen lds
	s_add_i32 s3, s3, s8
	s_mov_b32 m0, s6
	v_add_u32_e32 v149, 0x8000, v137
	buffer_load_dwordx4 v136, s[68:71], s3 offen lds
	s_or_b32 s3, s11, 0x80
	v_readfirstlane_b32 s11, v149
	v_add_u32_e32 v150, 0xa000, v137
	s_mov_b32 s6, s70
	s_mov_b32 s7, s71
	s_mov_b32 m0, s11
	v_readfirstlane_b32 s11, v150
	buffer_load_dwordx4 v136, s[4:7], s3 offen lds
	s_add_i32 s3, s3, s8
	s_mov_b32 m0, s11
	v_add_u32_e32 v152, 0x1c000, v137
	buffer_load_dwordx4 v136, s[4:7], s3 offen lds
	s_or_b32 s3, s10, 0x80
	v_readfirstlane_b32 s10, v152
	v_add_u32_e32 v154, 0x1e000, v137
	s_mov_b32 m0, s10
	v_readfirstlane_b32 s10, v154
	buffer_load_dwordx4 v136, s[68:71], s3 offen lds
	s_add_i32 s3, s3, s8
	s_mov_b32 m0, s10
	v_and_b32_e32 v3, 15, v0
	buffer_load_dwordx4 v136, s[68:71], s3 offen lds
	v_and_b32_e32 v5, 48, v0
	v_lshlrev_b32_e32 v6, 6, v3
	v_lshlrev_b32_e32 v8, 2, v0
	v_or_b32_e32 v7, v6, v5
	v_and_b32_e32 v8, 32, v8
	s_mov_b32 s3, 0x10000
	v_bitop3_b32 v9, v7, s3, v8 bitop3:0xde
	s_mov_b32 s3, 0x14000
	v_bitop3_b32 v10, v7, s3, v8 bitop3:0xde
	s_mov_b32 s3, 0x18000
	v_lshl_or_b32 v131, v2, 6, v3
	v_lshlrev_b32_e32 v3, 13, v2
	v_lshlrev_b32_e32 v2, 6, v0
	v_bfe_u32 v130, v0, 6, 2
	v_bitop3_b32 v11, v7, s3, v8 bitop3:0xde
	s_mov_b32 s3, 0x1c000
	v_and_b32_e32 v2, 0x3c0, v2
	s_lshl_b32 s19, s20, 1
	s_lshl_b32 s11, s17, 1
	s_lshl_b32 s21, s22, 1
	s_lshr_b32 s2, s24, 6
	v_lshlrev_b32_e32 v4, 12, v130
	v_bitop3_b32 v6, v6, v8, v5 bitop3:0x36
	v_bitop3_b32 v7, v7, s3, v8 bitop3:0xde
	v_bitop3_b32 v5, v2, v8, v5 bitop3:0x36
	v_or_b32_e32 v8, 0x800, v3
	v_or_b32_e32 v12, 0x1000, v3
	v_or_b32_e32 v13, 0x1800, v3
	s_add_i32 s3, s19, 0x180
	s_lshl_b32 s23, s24, 1
	s_add_i32 s10, s20, 0x80
	s_addk_i32 s11, 0x80
	s_addk_i32 s19, 0x80
	s_addk_i32 s21, 0x80
	v_mov_b32_e32 v2, 0
	s_add_i32 s2, s2, -2
	v_add_u32_e32 v153, 0xc000, v137
	v_add_u32_e32 v151, 0xe000, v137
	s_mul_i32 s3, s24, s3
	s_mul_i32 s10, s23, s10
	s_mul_i32 s11, s24, s11
	s_mul_i32 s17, s23, s17
	s_mul_i32 s19, s24, s19
	s_mul_i32 s20, s23, s20
	s_mul_i32 s21, s24, s21
	s_mul_i32 s22, s23, s22
	s_mov_b32 s23, 0
	v_add_u32_e32 v156, v9, v4
	v_add_u32_e32 v135, v6, v3
	v_add_u32_e32 v134, v5, v8
	v_add_u32_e32 v133, v5, v12
	v_add_u32_e32 v132, v5, v13
	v_add_u32_e32 v155, v10, v4
	v_add_u32_e32 v144, v11, v4
	v_add_u32_e32 v138, v7, v4
	s_mov_b32 s25, 0
	v_mov_b32_e32 v3, v2
	v_mov_b32_e32 v4, v2
	v_mov_b32_e32 v5, v2
	v_mov_b32_e32 v6, v2
	v_mov_b32_e32 v7, v2
	v_mov_b32_e32 v8, v2
	v_mov_b32_e32 v9, v2
	v_mov_b32_e32 v10, v2
	v_mov_b32_e32 v11, v2
	v_mov_b32_e32 v12, v2
	v_mov_b32_e32 v13, v2
	v_mov_b32_e32 v14, v2
	v_mov_b32_e32 v15, v2
	v_mov_b32_e32 v16, v2
	v_mov_b32_e32 v17, v2
	v_mov_b32_e32 v18, v2
	v_mov_b32_e32 v19, v2
	v_mov_b32_e32 v20, v2
	v_mov_b32_e32 v21, v2
	v_mov_b32_e32 v22, v2
	v_mov_b32_e32 v23, v2
	v_mov_b32_e32 v24, v2
	v_mov_b32_e32 v25, v2
	s_waitcnt vmcnt(18)
	v_mov_b32_e32 v26, v2
	v_mov_b32_e32 v27, v2
	v_mov_b32_e32 v28, v2
	v_mov_b32_e32 v29, v2
	s_waitcnt vmcnt(16)
	v_mov_b32_e32 v30, v2
	v_mov_b32_e32 v31, v2
	v_mov_b32_e32 v32, v2
	v_mov_b32_e32 v33, v2
	s_waitcnt vmcnt(14)
	v_mov_b32_e32 v34, v2
	v_mov_b32_e32 v35, v2
	v_mov_b32_e32 v36, v2
	v_mov_b32_e32 v37, v2
	v_mov_b32_e32 v38, v2
	v_mov_b32_e32 v39, v2
	v_mov_b32_e32 v40, v2
	v_mov_b32_e32 v41, v2
	v_mov_b32_e32 v42, v2
	v_mov_b32_e32 v43, v2
	v_mov_b32_e32 v44, v2
	v_mov_b32_e32 v45, v2
	v_mov_b32_e32 v46, v2
	v_mov_b32_e32 v47, v2
	v_mov_b32_e32 v48, v2
	v_mov_b32_e32 v49, v2
	v_mov_b32_e32 v50, v2
	v_mov_b32_e32 v51, v2
	v_mov_b32_e32 v52, v2
	v_mov_b32_e32 v53, v2
	v_mov_b32_e32 v54, v2
	v_mov_b32_e32 v55, v2
	v_mov_b32_e32 v56, v2
	v_mov_b32_e32 v57, v2
	v_mov_b32_e32 v58, v2
	v_mov_b32_e32 v59, v2
	v_mov_b32_e32 v60, v2
	v_mov_b32_e32 v61, v2
	v_mov_b32_e32 v62, v2
	v_mov_b32_e32 v63, v2
	v_mov_b32_e32 v64, v2
	v_mov_b32_e32 v65, v2
	v_mov_b32_e32 v66, v2
	v_mov_b32_e32 v67, v2
	v_mov_b32_e32 v68, v2
	v_mov_b32_e32 v69, v2
	v_mov_b32_e32 v70, v2
	v_mov_b32_e32 v71, v2
	v_mov_b32_e32 v72, v2
	v_mov_b32_e32 v73, v2
	v_mov_b32_e32 v74, v2
	v_mov_b32_e32 v75, v2
	v_mov_b32_e32 v76, v2
	v_mov_b32_e32 v77, v2
	v_mov_b32_e32 v78, v2
	v_mov_b32_e32 v79, v2
	v_mov_b32_e32 v80, v2
	v_mov_b32_e32 v81, v2
	v_mov_b32_e32 v82, v2
	v_mov_b32_e32 v83, v2
	v_mov_b32_e32 v84, v2
	v_mov_b32_e32 v85, v2
	v_mov_b32_e32 v86, v2
	v_mov_b32_e32 v87, v2
	v_mov_b32_e32 v88, v2
	v_mov_b32_e32 v89, v2
	v_mov_b32_e32 v90, v2
	v_mov_b32_e32 v91, v2
	v_mov_b32_e32 v92, v2
	v_mov_b32_e32 v93, v2
	v_mov_b32_e32 v94, v2
	v_mov_b32_e32 v95, v2
	v_mov_b32_e32 v96, v2
	v_mov_b32_e32 v97, v2
	v_mov_b32_e32 v98, v2
	v_mov_b32_e32 v99, v2
	v_mov_b32_e32 v100, v2
	v_mov_b32_e32 v101, v2
	v_mov_b32_e32 v102, v2
	v_mov_b32_e32 v103, v2
	v_mov_b32_e32 v104, v2
	v_mov_b32_e32 v105, v2
	v_mov_b32_e32 v106, v2
	v_mov_b32_e32 v107, v2
	v_mov_b32_e32 v108, v2
	v_mov_b32_e32 v109, v2
	v_mov_b32_e32 v110, v2
	v_mov_b32_e32 v111, v2
	v_mov_b32_e32 v112, v2
	v_mov_b32_e32 v113, v2
	v_mov_b32_e32 v114, v2
	v_mov_b32_e32 v115, v2
	v_mov_b32_e32 v116, v2
	v_mov_b32_e32 v117, v2
	v_mov_b32_e32 v118, v2
	v_mov_b32_e32 v119, v2
	v_mov_b32_e32 v120, v2
	v_mov_b32_e32 v121, v2
	v_mov_b32_e32 v122, v2
	v_mov_b32_e32 v123, v2
	v_mov_b32_e32 v124, v2
	v_mov_b32_e32 v125, v2
	v_mov_b32_e32 v126, v2
	v_mov_b32_e32 v127, v2
	v_mov_b32_e32 v128, v2
	v_mov_b32_e32 v129, v2
	s_waitcnt vmcnt(6)
	s_barrier
